# both S5 scan loops: recurrence step as four scalar fmas (two-deep dependency chain) instead of packed ops
# speedup vs baseline: 1.0044x; 1.0044x over previous
.LBB0_333:
	ds_read2_b32 v[52:53], v51 offset1:68
	ds_read2_b32 v[54:55], v51 offset0:136 offset1:204
	v_add_u32_e32 v58, 0x400, v51
	ds_read2_b32 v[56:57], v58 offset0:16 offset1:84
	ds_read2_b32 v[58:59], v58 offset0:152 offset1:220
	s_add_i32 s2, s2, 8
	s_waitcnt lgkmcnt(3)
	v_lshlrev_b32_e32 v62, 16, v52
	v_and_b32_e32 v63, 0xffff0000, v52
	v_fma_f32 v60, -v41, v45, v62
	v_fma_f32 v61, v41, v44, v63
	v_fma_f32 v44, v40, v44, v60
	v_fma_f32 v45, v40, v45, v61
	v_lshlrev_b32_e32 v62, 16, v53
	v_and_b32_e32 v63, 0xffff0000, v53
	v_fma_f32 v60, -v41, v45, v62
	v_fma_f32 v61, v41, v44, v63
	v_fma_f32 v44, v40, v44, v60
	v_fma_f32 v45, v40, v45, v61
	s_waitcnt lgkmcnt(2)
	v_lshlrev_b32_e32 v62, 16, v54
	v_and_b32_e32 v63, 0xffff0000, v54
	v_fma_f32 v60, -v41, v45, v62
	v_fma_f32 v61, v41, v44, v63
	v_fma_f32 v44, v40, v44, v60
	v_fma_f32 v45, v40, v45, v61
	v_lshlrev_b32_e32 v62, 16, v55
	v_and_b32_e32 v63, 0xffff0000, v55
	v_fma_f32 v60, -v41, v45, v62
	v_fma_f32 v61, v41, v44, v63
	v_fma_f32 v44, v40, v44, v60
	v_fma_f32 v45, v40, v45, v61
	s_waitcnt lgkmcnt(1)
	v_lshlrev_b32_e32 v62, 16, v56
	v_and_b32_e32 v63, 0xffff0000, v56
	v_fma_f32 v60, -v41, v45, v62
	v_fma_f32 v61, v41, v44, v63
	v_fma_f32 v44, v40, v44, v60
	v_fma_f32 v45, v40, v45, v61
	v_lshlrev_b32_e32 v62, 16, v57
	v_and_b32_e32 v63, 0xffff0000, v57
	v_fma_f32 v60, -v41, v45, v62
	v_fma_f32 v61, v41, v44, v63
	v_fma_f32 v44, v40, v44, v60
	v_fma_f32 v45, v40, v45, v61
	s_waitcnt lgkmcnt(0)
	v_lshlrev_b32_e32 v62, 16, v58
	v_and_b32_e32 v63, 0xffff0000, v58
	v_fma_f32 v60, -v41, v45, v62
	v_fma_f32 v61, v41, v44, v63
	v_fma_f32 v44, v40, v44, v60
	v_fma_f32 v45, v40, v45, v61
	v_lshlrev_b32_e32 v62, 16, v59
	v_and_b32_e32 v63, 0xffff0000, v59
	v_fma_f32 v60, -v41, v45, v62
	v_fma_f32 v61, v41, v44, v63
	v_fma_f32 v44, v40, v44, v60
	v_fma_f32 v45, v40, v45, v61
	v_add_u32_e32 v51, 0x880, v51
	s_cmp_lt_u32 s2, 24
	s_cbranch_scc1 .LBB0_333
	s_mov_b32 s19, 32
	s_mov_b64 s[2:3], 0
	s_and_b64 vcc, exec, s[16:17]
	s_cbranch_vccz .LBB0_332
	s_add_i32 s2, s18, s7
	s_ashr_i32 s3, s2, 31
	s_lshl_b64 s[2:3], s[2:3], 9
	v_lshl_add_u64 v[4:5], v[38:39], 0, s[2:3]
	s_mov_b32 s14, 1
	s_mov_b64 s[2:3], 0
	s_and_b64 vcc, exec, s[12:13]
	global_store_dwordx2 v[4:5], v[44:45], off
	s_cbranch_vccz .LBB0_331
	s_add_i32 s6, s6, s81
	s_cmpk_gt_i32 s6, 0xff
	s_cbranch_scc0 .LBB0_330

.LBB0_439:
	ds_read2_b32 v[122:123], v83 offset1:68
	ds_read2_b32 v[124:125], v83 offset0:136 offset1:204
	v_add_u32_e32 v121, 0x400, v83
	ds_read2_b32 v[126:127], v121 offset0:16 offset1:84
	ds_read2_b32 v[128:129], v121 offset0:152 offset1:220
	s_add_i32 s2, s2, 8
	s_waitcnt lgkmcnt(3)
	v_lshlrev_b32_e32 v136, 16, v122
	v_and_b32_e32 v137, 0xffff0000, v122
	v_fma_f32 v134, -v91, v93, v136
	v_fma_f32 v135, v91, v92, v137
	v_fma_f32 v92, v90, v92, v134
	v_fma_f32 v93, v90, v93, v135
	v_lshlrev_b32_e32 v136, 16, v123
	v_and_b32_e32 v137, 0xffff0000, v123
	v_fma_f32 v134, -v91, v93, v136
	v_fma_f32 v135, v91, v92, v137
	v_cvt_pk_bf16_f32 v130, v92, v93
	v_fma_f32 v92, v90, v92, v134
	v_fma_f32 v93, v90, v93, v135
	v_cvt_pk_bf16_f32 v131, v92, v93
	ds_write2_b32 v83, v130, v131 offset1:68
	s_waitcnt lgkmcnt(3)
	v_lshlrev_b32_e32 v136, 16, v124
	v_and_b32_e32 v137, 0xffff0000, v124
	v_fma_f32 v134, -v91, v93, v136
	v_fma_f32 v135, v91, v92, v137
	v_fma_f32 v92, v90, v92, v134
	v_fma_f32 v93, v90, v93, v135
	v_lshlrev_b32_e32 v136, 16, v125
	v_and_b32_e32 v137, 0xffff0000, v125
	v_fma_f32 v134, -v91, v93, v136
	v_fma_f32 v135, v91, v92, v137
	v_cvt_pk_bf16_f32 v132, v92, v93
	v_fma_f32 v92, v90, v92, v134
	v_fma_f32 v93, v90, v93, v135
	v_cvt_pk_bf16_f32 v133, v92, v93
	ds_write2_b32 v83, v132, v133 offset0:136 offset1:204
	s_waitcnt lgkmcnt(3)
	v_lshlrev_b32_e32 v136, 16, v126
	v_and_b32_e32 v137, 0xffff0000, v126
	v_fma_f32 v134, -v91, v93, v136
	v_fma_f32 v135, v91, v92, v137
	v_fma_f32 v92, v90, v92, v134
	v_fma_f32 v93, v90, v93, v135
	v_lshlrev_b32_e32 v136, 16, v127
	v_and_b32_e32 v137, 0xffff0000, v127
	v_fma_f32 v134, -v91, v93, v136
	v_fma_f32 v135, v91, v92, v137
	v_cvt_pk_bf16_f32 v130, v92, v93
	v_fma_f32 v92, v90, v92, v134
	v_fma_f32 v93, v90, v93, v135
	v_cvt_pk_bf16_f32 v131, v92, v93
	ds_write2_b32 v121, v130, v131 offset0:16 offset1:84
	s_waitcnt lgkmcnt(3)
	v_lshlrev_b32_e32 v136, 16, v128
	v_and_b32_e32 v137, 0xffff0000, v128
	v_fma_f32 v134, -v91, v93, v136
	v_fma_f32 v135, v91, v92, v137
	v_fma_f32 v92, v90, v92, v134
	v_fma_f32 v93, v90, v93, v135
	v_lshlrev_b32_e32 v136, 16, v129
	v_and_b32_e32 v137, 0xffff0000, v129
	v_fma_f32 v134, -v91, v93, v136
	v_fma_f32 v135, v91, v92, v137
	v_cvt_pk_bf16_f32 v132, v92, v93
	v_fma_f32 v92, v90, v92, v134
	v_fma_f32 v93, v90, v93, v135
	v_cvt_pk_bf16_f32 v133, v92, v93
	v_add_u32_e32 v83, 0x880, v83
	s_cmp_lt_u32 s2, 24
	ds_write2_b32 v121, v132, v133 offset0:152 offset1:220
	s_cbranch_scc1 .LBB0_439
	s_waitcnt lgkmcnt(0)
	ds_read_b128 v[122:125], v117 offset:32768
	ds_read_b128 v[126:129], v117 offset:32832
	v_or_b32_e32 v83, s14, v78
	v_mad_u32_u24 v83, v83, s15, v120
	s_mov_b32 s14, 32
	s_waitcnt lgkmcnt(1)
	v_mfma_f32_16x16x32_bf16 v[122:125], v[52:55], v[122:125], v[0:3]
	s_mov_b64 s[4:5], 0
	s_waitcnt lgkmcnt(0)
	v_mfma_f32_16x16x32_bf16 v[122:125], v[48:51], v[126:129], v[122:125]
	ds_read_b128 v[126:129], v117 offset:32896
	s_waitcnt lgkmcnt(0)
	v_mfma_f32_16x16x32_bf16 v[122:125], v[44:47], v[126:129], v[122:125]
	ds_read_b128 v[126:129], v117 offset:32960
	s_waitcnt lgkmcnt(0)
	v_mfma_f32_16x16x32_bf16 v[122:125], v[40:43], v[126:129], v[122:125]
	v_lshlrev_b32_e32 v126, 16, v102
	v_and_b32_e32 v127, 0xffff0000, v102
	s_nop 5
	v_pk_fma_f32 v[122:123], v[4:5], v[126:127], v[122:123]
	s_nop 0
	v_mul_f32_e32 v102, 0x3d372713, v122
	v_mul_f32_e32 v102, v122, v102
	v_fma_f32 v102, v122, v102, v122
	v_mul_f32_e32 v102, 0x3f4c422a, v102
	v_add_f32_e32 v102, v102, v102
	v_mul_f32_e32 v102, 0xbfb8aa3b, v102
	v_exp_f32_e32 v126, v102
	v_mul_f32_e32 v102, 0x3d372713, v123
	v_mul_f32_e32 v102, v123, v102
	v_fma_f32 v102, v123, v102, v123
	v_mul_f32_e32 v102, 0x3f4c422a, v102
	v_add_f32_e32 v102, v102, v102
	v_mul_f32_e32 v102, 0xbfb8aa3b, v102
	v_exp_f32_e32 v127, v102
	s_nop 0
	v_pk_add_f32 v[126:127], v[126:127], 1.0 op_sel_hi:[1,0]
	s_nop 0
	v_rcp_f32_e32 v127, v127
	v_rcp_f32_e32 v126, v126
	v_lshlrev_b32_e32 v102, 16, v103
	v_and_b32_e32 v103, 0xffff0000, v103
	v_pk_fma_f32 v[102:103], v[6:7], v[102:103], v[124:125]
	v_pk_mul_f32 v[122:123], v[122:123], v[126:127]
	v_mul_f32_e32 v121, 0x3d372713, v102
	v_mul_f32_e32 v121, v102, v121
	v_fma_f32 v121, v102, v121, v102
	v_mul_f32_e32 v121, 0x3f4c422a, v121
	v_add_f32_e32 v121, v121, v121
	v_mul_f32_e32 v121, 0xbfb8aa3b, v121
	v_exp_f32_e32 v124, v121
	v_mul_f32_e32 v121, 0x3d372713, v103
	v_mul_f32_e32 v121, v103, v121
	v_fma_f32 v121, v103, v121, v103
	v_mul_f32_e32 v121, 0x3f4c422a, v121
	v_add_f32_e32 v121, v121, v121
	v_mul_f32_e32 v121, 0xbfb8aa3b, v121
	v_exp_f32_e32 v125, v121
	v_cvt_pk_bf16_f32 v122, v122, v123
	v_pk_add_f32 v[124:125], v[124:125], 1.0 op_sel_hi:[1,0]
	s_nop 0
	v_rcp_f32_e32 v125, v125
	v_rcp_f32_e32 v124, v124
	s_nop 0
	v_pk_mul_f32 v[102:103], v[102:103], v[124:125]
	s_nop 0
	v_cvt_pk_bf16_f32 v123, v102, v103
	ds_write_b64 v83, v[122:123]
	ds_read_b128 v[122:125], v117 offset:37120
	ds_read_b128 v[126:129], v117 offset:37184
	s_waitcnt lgkmcnt(1)
	v_mfma_f32_16x16x32_bf16 v[122:125], v[52:55], v[122:125], v[0:3]
	v_lshlrev_b32_e32 v102, 16, v100
	v_and_b32_e32 v103, 0xffff0000, v100
	s_waitcnt lgkmcnt(0)
	v_mfma_f32_16x16x32_bf16 v[122:125], v[48:51], v[126:129], v[122:125]
	ds_read_b128 v[126:129], v117 offset:37248
	s_waitcnt lgkmcnt(0)
	v_mfma_f32_16x16x32_bf16 v[122:125], v[44:47], v[126:129], v[122:125]
	ds_read_b128 v[126:129], v117 offset:37312
	s_waitcnt lgkmcnt(0)
	v_mfma_f32_16x16x32_bf16 v[122:125], v[40:43], v[126:129], v[122:125]
	s_nop 7
	v_pk_fma_f32 v[102:103], v[4:5], v[102:103], v[122:123]
	s_nop 0
	v_mul_f32_e32 v100, 0x3d372713, v102
	v_mul_f32_e32 v100, v102, v100
	v_fma_f32 v100, v102, v100, v102
	v_mul_f32_e32 v100, 0x3f4c422a, v100
	v_add_f32_e32 v100, v100, v100
	v_mul_f32_e32 v100, 0xbfb8aa3b, v100
	v_exp_f32_e32 v122, v100
	v_mul_f32_e32 v100, 0x3d372713, v103
	v_mul_f32_e32 v100, v103, v100
	v_fma_f32 v100, v103, v100, v103
	v_mul_f32_e32 v100, 0x3f4c422a, v100
	v_add_f32_e32 v100, v100, v100
	v_mul_f32_e32 v100, 0xbfb8aa3b, v100
	v_exp_f32_e32 v123, v100
	s_nop 0
	v_pk_add_f32 v[122:123], v[122:123], 1.0 op_sel_hi:[1,0]
	s_nop 0
	v_rcp_f32_e32 v123, v123
	v_rcp_f32_e32 v122, v122
	v_lshlrev_b32_e32 v100, 16, v101
	v_and_b32_e32 v101, 0xffff0000, v101
	v_pk_fma_f32 v[100:101], v[6:7], v[100:101], v[124:125]
	v_pk_mul_f32 v[102:103], v[102:103], v[122:123]
	v_mul_f32_e32 v121, 0x3d372713, v100
	v_mul_f32_e32 v121, v100, v121
	v_fma_f32 v121, v100, v121, v100
	v_mul_f32_e32 v121, 0x3f4c422a, v121
	v_add_f32_e32 v121, v121, v121
	v_mul_f32_e32 v121, 0xbfb8aa3b, v121
	v_exp_f32_e32 v122, v121
	v_mul_f32_e32 v121, 0x3d372713, v101
	v_mul_f32_e32 v121, v101, v121
	v_fma_f32 v121, v101, v121, v101
	v_mul_f32_e32 v121, 0x3f4c422a, v121
	v_add_f32_e32 v121, v121, v121
	v_mul_f32_e32 v121, 0xbfb8aa3b, v121
	v_exp_f32_e32 v123, v121
	v_cvt_pk_bf16_f32 v102, v102, v103
	v_pk_add_f32 v[122:123], v[122:123], 1.0 op_sel_hi:[1,0]
	s_nop 0
	v_rcp_f32_e32 v123, v123
	v_rcp_f32_e32 v122, v122
	s_nop 0
	v_pk_mul_f32 v[100:101], v[100:101], v[122:123]
	s_and_b64 vcc, exec, s[12:13]
	v_cvt_pk_bf16_f32 v103, v100, v101
	ds_write_b64 v83, v[102:103] offset:8448
	s_nop 7
	s_cbranch_vccz .LBB0_438
	s_and_b64 vcc, exec, s[24:25]
	s_cbranch_vccz .LBB0_432
	s_ashr_i32 s29, s28, 31
	s_lshl_b64 s[2:3], s[28:29], 8
	v_lshl_add_u64 v[4:5], v[88:89], 0, s[2:3]
	v_add_co_u32_e32 v6, vcc, 0x645c000, v4
	s_nop 1
	v_addc_co_u32_e32 v7, vcc, 0, v5, vcc
	v_add_co_u32_e32 v4, vcc, 0x667c000, v4
	global_store_dword v[6:7], v92, off
	s_nop 0
	v_addc_co_u32_e32 v5, vcc, 0, v5, vcc
	global_store_dword v[4:5], v93, off
	s_branch .LBB0_432
